# epilogue rs-load waits counted (vmcnt(N) not 0) in SwiGLU/Scale epilogues, flat->global; plus sgemm MODE1 pipelined loads
# speedup vs baseline: 1.0152x; 1.0152x over previous
; #define LAS __attribute__((address_space(3)))
; __device__ __forceinline__ unsigned cvt_pk_bf16(float lo, float hi) { unsigned r; asm volatile("v_cvt_pk_bf16_f32 %0, %1, %2" : "=v"(r) : "v"(lo), "v"(hi)); return r; }
; __device__ __forceinline__ void rs_issue(const float* ssq, int rbase, RsLoad& L) {
;     const int lane = threadIdx.x & 63;
;     const f32x4* p0 = (const f32x4*)(ssq + (size_t)(rbase + lane) * 16); const f32x4* p1 = (const f32x4*)(ssq + (size_t)(rbase + 128 + lane) * 16);
;     L.a0 = p0[0]; L.b0 = p0[1]; L.c0 = p0[2]; L.d0 = p0[3]; L.a1 = p1[0]; L.b1 = p1[1]; L.c1 = p1[2]; L.d1 = p1[3];
;     asm volatile("" ::: "memory");
; }
;     __device__ __forceinline__ void operator()(Acc& acc, const Unit& u, int wr, int wc, int fr, int fq, LAS unsigned char*, const LAS float* rst) const {
;         const int row0 = u.pm * 256 + wr * 64 + fr, col0 = u.pn * 256 + wc * 32 + 8 * fq;
;         float rsv[2][4];
; #pragma unroll
;         for (int m = 0; m < 4; ++m) { rsv[0][m] = ssq ? rst[m * 16 + fr] : 1.0f; rsv[1][m] = ssq ? rst[64 + m * 16 + fr] : 1.0f; }
; #pragma unroll
;         for (int ai = 0; ai < 2; ++ai)
; #pragma unroll
;             for (int m = 0; m < 4; ++m) {
;                 const int row = row0 + ai * 128 + m * 16; const float rs = rsv[ai][m];
; #pragma unroll
;                 for (int bj = 0; bj < 2; ++bj) { const f32x4 v0 = acc[ai][bj][m][0] * rs, v1 = acc[ai][bj][m][1] * rs;
;                     u32x4 w; w.x = cvt_pk_bf16(v0[0], v0[1]); w.y = cvt_pk_bf16(v0[2], v0[3]); w.z = cvt_pk_bf16(v1[0], v1[1]); w.w = cvt_pk_bf16(v1[2], v1[3]);
;                     *(u32x4*)(O + (size_t)row * ldc + col0 + bj * 128) = w; }
;             }
.LBB0_633:
	s_and_b64 vcc, exec, s[0:1]
	s_cbranch_vccz .LBB0_645
	s_and_b64 s[0:1], s[10:11], exec
	s_cselect_b32 s0, s66, s62
	v_lshl_add_u32 v130, s0, 8, v182
	v_ashrrev_i32_e32 v131, 31, v130
	v_lshlrev_b64 v[132:133], 6, v[130:131]
	v_add_u32_e32 v130, 0x80, v130
	v_ashrrev_i32_e32 v131, 31, v130
	v_lshlrev_b64 v[130:131], 6, v[130:131]
	v_lshl_add_u64 v[132:133], s[30:31], 0, v[132:133]
	v_lshl_add_u64 v[134:135], s[30:31], 0, v[130:131]
	global_load_dwordx4 v[154:157], v[132:133], off
	global_load_dwordx4 v[158:161], v[132:133], off offset:16
	global_load_dwordx4 v[146:149], v[132:133], off offset:32
	global_load_dwordx4 v[150:153], v[132:133], off offset:48
	global_load_dwordx4 v[138:141], v[134:135], off
	global_load_dwordx4 v[142:145], v[134:135], off offset:16
	s_nop 0
	global_load_dwordx4 v[130:133], v[134:135], off offset:32
	s_nop 0
	global_load_dwordx4 v[134:137], v[134:135], off offset:48
	ds_read2_b32 v[192:193], v181 offset1:16
	ds_read2_b32 v[176:177], v181 offset0:64 offset1:80
	ds_read2_b32 v[194:195], v181 offset0:32 offset1:48
	ds_read2_b32 v[174:175], v181 offset0:96 offset1:112
	v_lshl_add_u32 v190, s52, 8, v179
	v_ashrrev_i32_e32 v200, 31, v190
	s_waitcnt lgkmcnt(0)
	v_pk_mul_f32 v[126:127], v[126:127], v[192:193] op_sel_hi:[1,0]
	v_pk_mul_f32 v[198:199], v[124:125], v[192:193] op_sel_hi:[1,0]
	v_pk_mul_f32 v[122:123], v[122:123], v[192:193] op_sel_hi:[1,0]
	v_lshl_or_b32 v196, s42, 8, v183
	v_pk_mul_f32 v[128:129], v[128:129], v[192:193] op_sel_hi:[1,0]
	v_cvt_pk_bf16_f32 v124, v126, v127
	v_ashrrev_i32_e32 v197, 31, v196
	v_cvt_pk_bf16_f32 v125, v128, v129
	v_cvt_pk_bf16_f32 v126, v122, v123
	v_cvt_pk_bf16_f32 v127, v198, v199
	v_mul_lo_u32 v198, v200, s56
	v_mad_u64_u32 v[122:123], s[0:1], v190, s56, 0
	v_add_u32_e32 v123, v123, v198
	v_lshl_add_u64 v[128:129], v[122:123], 1, s[34:35]
	v_lshlrev_b64 v[122:123], 1, v[196:197]
	v_lshl_add_u64 v[128:129], v[128:129], 0, v[122:123]
	global_store_dwordx4 v[128:129], v[124:127], off
	v_pk_mul_f32 v[120:121], v[120:121], v[192:193] op_sel_hi:[1,0]
	v_pk_mul_f32 v[118:119], v[118:119], v[192:193] op_sel_hi:[1,0]
	v_pk_mul_f32 v[124:125], v[112:113], v[192:193] op_sel_hi:[1,0]
	v_pk_mul_f32 v[112:113], v[110:111], v[192:193] op_sel_hi:[1,0]
	v_cvt_pk_bf16_f32 v110, v118, v119
	v_cvt_pk_bf16_f32 v111, v120, v121
	v_pk_mul_f32 v[88:89], v[88:89], v[194:195] op_sel_hi:[1,0]
	v_cvt_pk_bf16_f32 v112, v112, v113
	v_cvt_pk_bf16_f32 v113, v124, v125
	global_store_dwordx4 v[128:129], v[110:113], off offset:256
	v_pk_mul_f32 v[86:87], v[86:87], v[194:195] op_sel_hi:[1,0]
	v_pk_mul_f32 v[62:63], v[62:63], v[176:177] op_sel_hi:[1,0]
	v_or_b32_e32 v111, 16, v190
	v_mov_b32_e32 v110, v193
	v_pk_mul_f32 v[112:113], v[116:117], v[110:111] op_sel_hi:[1,0]
	v_pk_mul_f32 v[114:115], v[114:115], v[110:111] op_sel_hi:[1,0]
	v_pk_mul_f32 v[116:117], v[108:109], v[110:111] op_sel_hi:[1,0]
	v_pk_mul_f32 v[108:109], v[106:107], v[110:111] op_sel_hi:[1,0]
	v_cvt_pk_bf16_f32 v106, v114, v115
	v_cvt_pk_bf16_f32 v107, v112, v113
	v_mad_u64_u32 v[112:113], s[0:1], v111, s56, 0
	v_add_u32_e32 v113, v113, v198
	v_lshl_add_u64 v[112:113], v[112:113], 1, s[34:35]
	v_lshl_add_u64 v[112:113], v[112:113], 0, v[122:123]
	v_cvt_pk_bf16_f32 v108, v108, v109
	v_cvt_pk_bf16_f32 v109, v116, v117
	global_store_dwordx4 v[112:113], v[106:109], off
	v_pk_mul_f32 v[104:105], v[104:105], v[110:111] op_sel_hi:[1,0]
	v_pk_mul_f32 v[102:103], v[102:103], v[110:111] op_sel_hi:[1,0]
	v_pk_mul_f32 v[106:107], v[96:97], v[110:111] op_sel_hi:[1,0]
	v_pk_mul_f32 v[96:97], v[94:95], v[110:111] op_sel_hi:[1,0]
	v_cvt_pk_bf16_f32 v94, v102, v103
	v_cvt_pk_bf16_f32 v95, v104, v105
	v_or_b32_e32 v102, 32, v190
	v_cvt_pk_bf16_f32 v96, v96, v97
	v_cvt_pk_bf16_f32 v97, v106, v107
	global_store_dwordx4 v[112:113], v[94:97], off offset:256
	v_pk_mul_f32 v[64:65], v[64:65], v[176:177] op_sel_hi:[1,0]
	v_pk_mul_f32 v[56:57], v[56:57], v[176:177] op_sel_hi:[1,0]
	v_pk_mul_f32 v[94:95], v[100:101], v[194:195] op_sel_hi:[1,0]
	v_pk_mul_f32 v[96:97], v[98:99], v[194:195] op_sel_hi:[1,0]
	v_pk_mul_f32 v[98:99], v[92:93], v[194:195] op_sel_hi:[1,0]
	v_pk_mul_f32 v[92:93], v[90:91], v[194:195] op_sel_hi:[1,0]
	v_cvt_pk_bf16_f32 v90, v96, v97
	v_cvt_pk_bf16_f32 v91, v94, v95
	v_mad_u64_u32 v[94:95], s[0:1], v102, s56, 0
	v_add_u32_e32 v95, v95, v198
	v_lshl_add_u64 v[94:95], v[94:95], 1, s[34:35]
	v_lshl_add_u64 v[94:95], v[94:95], 0, v[122:123]
	v_cvt_pk_bf16_f32 v92, v92, v93
	v_cvt_pk_bf16_f32 v93, v98, v99
	global_store_dwordx4 v[94:95], v[90:93], off
	v_pk_mul_f32 v[54:55], v[54:55], v[176:177] op_sel_hi:[1,0]
	v_pk_mul_f32 v[24:25], v[24:25], v[174:175] op_sel_hi:[1,0]
	v_pk_mul_f32 v[90:91], v[80:81], v[194:195] op_sel_hi:[1,0]
	v_pk_mul_f32 v[80:81], v[78:79], v[194:195] op_sel_hi:[1,0]
	v_cvt_pk_bf16_f32 v78, v86, v87
	v_cvt_pk_bf16_f32 v79, v88, v89
	v_pk_mul_f32 v[22:23], v[22:23], v[174:175] op_sel_hi:[1,0]
	v_cvt_pk_bf16_f32 v80, v80, v81
	v_cvt_pk_bf16_f32 v81, v90, v91
	global_store_dwordx4 v[94:95], v[78:81], off offset:256
	s_nop 1
	v_or_b32_e32 v79, 48, v190
	v_mov_b32_e32 v78, v195
	v_pk_mul_f32 v[80:81], v[84:85], v[78:79] op_sel_hi:[1,0]
	v_pk_mul_f32 v[82:83], v[82:83], v[78:79] op_sel_hi:[1,0]
	v_pk_mul_f32 v[84:85], v[76:77], v[78:79] op_sel_hi:[1,0]
	v_pk_mul_f32 v[76:77], v[74:75], v[78:79] op_sel_hi:[1,0]
	v_cvt_pk_bf16_f32 v74, v82, v83
	v_cvt_pk_bf16_f32 v75, v80, v81
	v_mad_u64_u32 v[80:81], s[0:1], v79, s56, 0
	v_add_u32_e32 v81, v81, v198
	v_lshl_add_u64 v[80:81], v[80:81], 1, s[34:35]
	v_lshl_add_u64 v[80:81], v[80:81], 0, v[122:123]
	v_cvt_pk_bf16_f32 v76, v76, v77
	v_cvt_pk_bf16_f32 v77, v84, v85
; __device__ __forceinline__ unsigned cvt_pk_bf16(float lo, float hi) { unsigned r; asm volatile("v_cvt_pk_bf16_f32 %0, %1, %2" : "=v"(r) : "v"(lo), "v"(hi)); return r; }
; __device__ __forceinline__ void rs_reduce(const RsLoad& L, float& r0, float& r1) {
;     const f32x4 t0 = (L.a0 + L.b0) + (L.c0 + L.d0), t1 = (L.a1 + L.b1) + (L.c1 + L.d1);
;     r0 = rsqrtf(((t0.x + t0.y) + (t0.z + t0.w)) * (1.0f / 1024.0f) + EPS); r1 = rsqrtf(((t1.x + t1.y) + (t1.z + t1.w)) * (1.0f / 1024.0f) + EPS);
; }
; __device__ __forceinline__ void rs_spread(float r0, float r1, int fr, float (&rs)[2][4]) {
;     __device__ __forceinline__ void operator()(Acc& acc, const Unit& u, int wr, int wc, int fr, int fq, LAS unsigned char*, const LAS float* rst) const {
;     ...
;             for (int m = 0; m < 4; ++m) {
;                 const int row = row0 + ai * 128 + m * 16; const float rs = rsv[ai][m];
; #pragma unroll
;                 for (int bj = 0; bj < 2; ++bj) { const f32x4 v0 = acc[ai][bj][m][0] * rs, v1 = acc[ai][bj][m][1] * rs;
;                     u32x4 w; w.x = cvt_pk_bf16(v0[0], v0[1]); w.y = cvt_pk_bf16(v0[2], v0[3]); w.z = cvt_pk_bf16(v1[0], v1[1]); w.w = cvt_pk_bf16(v1[2], v1[3]);
;                     *(u32x4*)(O + (size_t)row * ldc + col0 + bj * 128) = w; }
;             }
	global_store_dwordx4 v[80:81], v[74:77], off
	v_pk_mul_f32 v[72:73], v[72:73], v[78:79] op_sel_hi:[1,0]
	v_pk_mul_f32 v[70:71], v[70:71], v[78:79] op_sel_hi:[1,0]
	v_pk_mul_f32 v[74:75], v[68:69], v[78:79] op_sel_hi:[1,0]
	v_pk_mul_f32 v[68:69], v[66:67], v[78:79] op_sel_hi:[1,0]
	v_cvt_pk_bf16_f32 v66, v70, v71
	v_cvt_pk_bf16_f32 v67, v72, v73
	s_nop 0
	v_cvt_pk_bf16_f32 v68, v68, v69
	v_cvt_pk_bf16_f32 v69, v74, v75
	global_store_dwordx4 v[80:81], v[66:69], off offset:256
	s_nop 1
	v_add_u32_e32 v68, 0x80, v190
	v_pk_mul_f32 v[66:67], v[60:61], v[176:177] op_sel_hi:[1,0]
	v_pk_mul_f32 v[60:61], v[58:59], v[176:177] op_sel_hi:[1,0]
	v_cvt_pk_bf16_f32 v58, v62, v63
	v_mad_u64_u32 v[62:63], s[0:1], v68, s56, 0
	v_ashrrev_i32_e32 v69, 31, v68
	v_cvt_pk_bf16_f32 v59, v64, v65
	v_mov_b32_e32 v64, v63
	v_mad_u64_u32 v[64:65], s[0:1], v69, s56, v[64:65]
	v_mov_b32_e32 v63, v64
	v_lshl_add_u64 v[62:63], v[62:63], 1, s[34:35]
	v_lshl_add_u64 v[62:63], v[62:63], 0, v[122:123]
	v_cvt_pk_bf16_f32 v60, v60, v61
	v_cvt_pk_bf16_f32 v61, v66, v67
	global_store_dwordx4 v[62:63], v[58:61], off
	s_nop 1
	v_pk_mul_f32 v[58:59], v[48:49], v[176:177] op_sel_hi:[1,0]
	v_pk_mul_f32 v[48:49], v[46:47], v[176:177] op_sel_hi:[1,0]
	v_cvt_pk_bf16_f32 v46, v54, v55
	v_cvt_pk_bf16_f32 v47, v56, v57
	s_nop 0
	v_cvt_pk_bf16_f32 v48, v48, v49
	v_cvt_pk_bf16_f32 v49, v58, v59
	global_store_dwordx4 v[62:63], v[46:49], off offset:256
	s_nop 1
	v_add_u32_e32 v47, 0x90, v190
	v_mov_b32_e32 v46, v177
	v_pk_mul_f32 v[48:49], v[52:53], v[46:47] op_sel_hi:[1,0]
	v_pk_mul_f32 v[50:51], v[50:51], v[46:47] op_sel_hi:[1,0]
	v_pk_mul_f32 v[52:53], v[44:45], v[46:47] op_sel_hi:[1,0]
	v_pk_mul_f32 v[44:45], v[42:43], v[46:47] op_sel_hi:[1,0]
	v_cvt_pk_bf16_f32 v42, v50, v51
	v_cvt_pk_bf16_f32 v43, v48, v49
	v_mad_u64_u32 v[48:49], s[0:1], v47, s56, 0
	v_ashrrev_i32_e32 v54, 31, v47
	v_mov_b32_e32 v50, v49
	v_mad_u64_u32 v[50:51], s[0:1], v54, s56, v[50:51]
	v_mov_b32_e32 v49, v50
	v_lshl_add_u64 v[48:49], v[48:49], 1, s[34:35]
	v_lshl_add_u64 v[48:49], v[48:49], 0, v[122:123]
	v_cvt_pk_bf16_f32 v44, v44, v45
	v_cvt_pk_bf16_f32 v45, v52, v53
	global_store_dwordx4 v[48:49], v[42:45], off
	v_pk_mul_f32 v[40:41], v[40:41], v[46:47] op_sel_hi:[1,0]
	v_pk_mul_f32 v[38:39], v[38:39], v[46:47] op_sel_hi:[1,0]
	v_pk_mul_f32 v[42:43], v[32:33], v[46:47] op_sel_hi:[1,0]
	v_pk_mul_f32 v[32:33], v[30:31], v[46:47] op_sel_hi:[1,0]
	v_cvt_pk_bf16_f32 v30, v38, v39
	v_cvt_pk_bf16_f32 v31, v40, v41
	v_add_u32_e32 v38, 0xa0, v190
	v_cvt_pk_bf16_f32 v32, v32, v33
	v_cvt_pk_bf16_f32 v33, v42, v43
	global_store_dwordx4 v[48:49], v[30:33], off offset:256
	v_ashrrev_i32_e32 v39, 31, v38
	s_nop 0
	v_pk_mul_f32 v[30:31], v[36:37], v[174:175] op_sel_hi:[1,0]
	v_pk_mul_f32 v[32:33], v[34:35], v[174:175] op_sel_hi:[1,0]
	v_pk_mul_f32 v[34:35], v[28:29], v[174:175] op_sel_hi:[1,0]
	v_pk_mul_f32 v[28:29], v[26:27], v[174:175] op_sel_hi:[1,0]
	v_cvt_pk_bf16_f32 v26, v32, v33
	v_cvt_pk_bf16_f32 v27, v30, v31
	v_mad_u64_u32 v[30:31], s[0:1], v38, s56, 0
	v_mov_b32_e32 v32, v31
	v_mad_u64_u32 v[32:33], s[0:1], v39, s56, v[32:33]
	v_mov_b32_e32 v31, v32
	v_lshl_add_u64 v[30:31], v[30:31], 1, s[34:35]
	v_lshl_add_u64 v[30:31], v[30:31], 0, v[122:123]
	v_cvt_pk_bf16_f32 v28, v28, v29
	v_cvt_pk_bf16_f32 v29, v34, v35
	global_store_dwordx4 v[30:31], v[26:29], off
	s_nop 1
	v_pk_mul_f32 v[26:27], v[16:17], v[174:175] op_sel_hi:[1,0]
	v_pk_mul_f32 v[16:17], v[14:15], v[174:175] op_sel_hi:[1,0]
	v_cvt_pk_bf16_f32 v14, v22, v23
	v_cvt_pk_bf16_f32 v15, v24, v25
	s_nop 0
	v_cvt_pk_bf16_f32 v16, v16, v17
	v_cvt_pk_bf16_f32 v17, v26, v27
	global_store_dwordx4 v[30:31], v[14:17], off offset:256
	s_nop 1
	v_add_u32_e32 v15, 0xb0, v190
	v_mov_b32_e32 v14, v175
	v_pk_mul_f32 v[16:17], v[20:21], v[14:15] op_sel_hi:[1,0]
	v_pk_mul_f32 v[18:19], v[18:19], v[14:15] op_sel_hi:[1,0]
	v_pk_mul_f32 v[20:21], v[12:13], v[14:15] op_sel_hi:[1,0]
	v_pk_mul_f32 v[12:13], v[10:11], v[14:15] op_sel_hi:[1,0]
	v_cvt_pk_bf16_f32 v10, v18, v19
	v_cvt_pk_bf16_f32 v11, v16, v17
	v_mad_u64_u32 v[16:17], s[0:1], v15, s56, 0
	v_ashrrev_i32_e32 v22, 31, v15
	v_mov_b32_e32 v18, v17
	v_mad_u64_u32 v[18:19], s[0:1], v22, s56, v[18:19]
	v_mov_b32_e32 v17, v18
	v_lshl_add_u64 v[16:17], v[16:17], 1, s[34:35]
	v_lshl_add_u64 v[16:17], v[16:17], 0, v[122:123]
	v_cvt_pk_bf16_f32 v12, v12, v13
	v_cvt_pk_bf16_f32 v13, v20, v21
	global_store_dwordx4 v[16:17], v[10:13], off
	v_pk_mul_f32 v[8:9], v[8:9], v[14:15] op_sel_hi:[1,0]
	v_pk_mul_f32 v[6:7], v[6:7], v[14:15] op_sel_hi:[1,0]
	v_pk_mul_f32 v[10:11], v[4:5], v[14:15] op_sel_hi:[1,0]
	v_pk_mul_f32 v[4:5], v[2:3], v[14:15] op_sel_hi:[1,0]
	v_cvt_pk_bf16_f32 v2, v6, v7
	v_cvt_pk_bf16_f32 v3, v8, v9
	s_waitcnt vmcnt(15)
	v_pk_add_f32 v[6:7], v[156:157], v[160:161]
	v_cvt_pk_bf16_f32 v4, v4, v5
	v_cvt_pk_bf16_f32 v5, v10, v11
	v_pk_add_f32 v[8:9], v[154:155], v[158:159]
	v_pk_add_f32 v[10:11], v[148:149], v[152:153]
	v_pk_add_f32 v[12:13], v[146:147], v[150:151]
	v_pk_add_f32 v[6:7], v[6:7], v[10:11]
	v_pk_add_f32 v[8:9], v[8:9], v[12:13]
	v_pk_add_f32 v[10:11], v[140:141], v[144:145]
	v_pk_add_f32 v[12:13], v[138:139], v[142:143]
	v_pk_add_f32 v[14:15], v[132:133], v[136:137]
	v_pk_add_f32 v[18:19], v[130:131], v[134:135]
	v_pk_add_f32 v[10:11], v[10:11], v[14:15]
	v_pk_add_f32 v[12:13], v[12:13], v[18:19]
	v_pk_mov_b32 v[14:15], v[8:9], v[6:7] op_sel:[1,0]
	v_mov_b32_e32 v9, v7
	v_pk_add_f32 v[6:7], v[14:15], v[8:9]
	v_pk_mov_b32 v[8:9], v[12:13], v[10:11] op_sel:[1,0]
	v_mov_b32_e32 v13, v11
	v_pk_add_f32 v[8:9], v[8:9], v[12:13]
	v_mov_b32_e32 v11, v6
	v_mov_b32_e32 v10, v8
	v_mov_b32_e32 v6, v9
	v_pk_add_f32 v[6:7], v[10:11], v[6:7]
	global_store_dwordx4 v[16:17], v[2:5], off offset:256
	v_pk_fma_f32 v[6:7], v[6:7], s[82:83], v[162:163] op_sel_hi:[1,0,0]
	s_nop 0
	v_mul_f32_e32 v8, 0x4b800000, v7
	v_cmp_gt_f32_e32 vcc, s69, v7
	v_cmp_gt_f32_e64 s[0:1], s69, v6
	s_nop 0
	v_cndmask_b32_e32 v7, v7, v8, vcc
	v_mul_f32_e32 v8, 0x4b800000, v6
	v_cndmask_b32_e64 v6, v6, v8, s[0:1]
	v_rsq_f32_e32 v7, v7
	v_rsq_f32_e32 v6, v6
	v_mul_f32_e32 v2, 0x45800000, v7
	v_mul_f32_e32 v3, 0x45800000, v6
	v_cndmask_b32_e32 v2, v7, v2, vcc
	v_cndmask_b32_e64 v3, v6, v3, s[0:1]
	ds_write2st64_b32 v178, v2, v3 offset1:1
	s_and_b64 vcc, exec, s[4:5]
	s_mov_b64 s[0:1], -1
	s_cbranch_vccnz .LBB0_616
	s_branch .LBB0_646

; #define LAS __attribute__((address_space(3)))
; __device__ __forceinline__ unsigned cvt_pk_bf16(float lo, float hi) { unsigned r; asm volatile("v_cvt_pk_bf16_f32 %0, %1, %2" : "=v"(r) : "v"(lo), "v"(hi)); return r; }
; __device__ __forceinline__ void rs_issue(const float* ssq, int rbase, RsLoad& L) {
;     const int lane = threadIdx.x & 63;
;     const f32x4* p0 = (const f32x4*)(ssq + (size_t)(rbase + lane) * 16); const f32x4* p1 = (const f32x4*)(ssq + (size_t)(rbase + 128 + lane) * 16);
;     L.a0 = p0[0]; L.b0 = p0[1]; L.c0 = p0[2]; L.d0 = p0[3]; L.a1 = p1[0]; L.b1 = p1[1]; L.c1 = p1[2]; L.d1 = p1[3];
;     asm volatile("" ::: "memory");
; }
;     __device__ __forceinline__ void operator()(Acc& acc, const Unit& u, int wr, int wc, int fr, int fq, LAS unsigned char*, const LAS float* rst) const {
;         const int row0 = u.pm * 256 + wr * 64 + fr, col0 = u.pn * 128 + wc * 32 + 8 * fq;
;         float rsv[2][4];
; #pragma unroll
;         for (int m = 0; m < 4; ++m) { rsv[0][m] = rst[m * 16 + fr]; rsv[1][m] = rst[64 + m * 16 + fr]; }
; #pragma unroll
;         for (int ai = 0; ai < 2; ++ai)
; #pragma unroll
;             for (int m = 0; m < 4; ++m) {
;                 const int row = row0 + ai * 128 + m * 16; const float rs = rsv[ai][m];
;                 const float cexp = -1.4426950408889634f * rs, rs2 = rs * rs;
;                 unsigned w[4];
; #pragma unroll
;                 for (int n = 0; n < 2; ++n)
; #pragma unroll
;                     for (int p = 0; p < 2; ++p) { const f32x2 g2 = {acc[ai][0][m][n][2 * p], acc[ai][0][m][n][2 * p + 1]}, u2 = {acc[ai][1][m][n][2 * p], acc[ai][1][m][n][2 * p + 1]};
;                         f32x2 e2 = g2 * cexp; e2.x = __builtin_amdgcn_exp2f(e2.x); e2.y = __builtin_amdgcn_exp2f(e2.y);
;                         const f32x2 d2 = e2 + 1.0f; f32x2 r2; r2.x = __builtin_amdgcn_rcpf(d2.x); r2.y = __builtin_amdgcn_rcpf(d2.y);
;                         const f32x2 o2 = ((g2 * u2) * rs2) * r2; w[n * 2 + p] = cvt_pk_bf16(o2.x, o2.y); }
;                 *(u32x4*)(O + (size_t)row * FF + col0) = (u32x4){w[0], w[1], w[2], w[3]};
;             }
.LBB0_777:
	v_lshl_add_u32 v130, s93, 8, v192
	v_ashrrev_i32_e32 v131, 31, v130
	v_lshlrev_b64 v[132:133], 6, v[130:131]
	v_add_u32_e32 v130, 0x80, v130
	v_ashrrev_i32_e32 v131, 31, v130
	v_lshlrev_b64 v[130:131], 6, v[130:131]
	v_lshl_add_u64 v[132:133], s[12:13], 0, v[132:133]
	v_lshl_add_u64 v[134:135], s[12:13], 0, v[130:131]
	global_load_dwordx4 v[154:157], v[132:133], off
	global_load_dwordx4 v[158:161], v[132:133], off offset:16
	global_load_dwordx4 v[146:149], v[132:133], off offset:32
	global_load_dwordx4 v[150:153], v[132:133], off offset:48
	global_load_dwordx4 v[138:141], v[134:135], off
	global_load_dwordx4 v[142:145], v[134:135], off offset:16
	s_nop 0
	global_load_dwordx4 v[130:133], v[134:135], off offset:32
	s_nop 0
	global_load_dwordx4 v[134:137], v[134:135], off offset:48
	ds_read2_b32 v[196:197], v191 offset1:16
	ds_read2_b32 v[176:177], v191 offset0:64 offset1:80
	ds_read2_b32 v[178:179], v191 offset0:32 offset1:48
	v_pk_mul_f32 v[124:125], v[128:129], v[124:125]
	v_pk_mul_f32 v[116:117], v[120:121], v[116:117]
	s_waitcnt lgkmcnt(0)
	v_mul_f32_e32 v198, 0xbfb8aa3b, v196
	v_pk_mul_f32 v[126:127], v[126:127], v[198:199] op_sel_hi:[1,0]
	v_pk_mul_f32 v[128:129], v[128:129], v[198:199] op_sel_hi:[1,0]
	v_exp_f32_e32 v200, v126
	v_exp_f32_e32 v201, v127
	v_exp_f32_e32 v128, v128
	v_exp_f32_e32 v129, v129
	v_mul_f32_e32 v196, v196, v196
	v_pk_add_f32 v[200:201], v[200:201], 1.0 op_sel_hi:[1,0]
	v_pk_mul_f32 v[122:123], v[122:123], v[196:197] op_sel_hi:[1,0]
	v_pk_add_f32 v[128:129], v[128:129], 1.0 op_sel_hi:[1,0]
	v_rcp_f32_e32 v200, v200
	v_rcp_f32_e32 v201, v201
	v_rcp_f32_e32 v128, v128
	v_rcp_f32_e32 v129, v129
	v_pk_mul_f32 v[118:119], v[118:119], v[198:199] op_sel_hi:[1,0]
	v_pk_mul_f32 v[124:125], v[124:125], v[196:197] op_sel_hi:[1,0]
	v_pk_mul_f32 v[122:123], v[122:123], v[200:201]
	v_exp_f32_e32 v118, v118
	v_exp_f32_e32 v119, v119
	v_pk_mul_f32 v[124:125], v[124:125], v[128:129]
	ds_read2_b32 v[126:127], v191 offset0:96 offset1:112
	v_cvt_pk_bf16_f32 v122, v122, v123
	v_cvt_pk_bf16_f32 v123, v124, v125
	v_pk_mul_f32 v[124:125], v[120:121], v[198:199] op_sel_hi:[1,0]
	v_pk_add_f32 v[118:119], v[118:119], 1.0 op_sel_hi:[1,0]
	v_exp_f32_e32 v124, v124
	v_exp_f32_e32 v125, v125
	v_rcp_f32_e32 v118, v118
	v_rcp_f32_e32 v119, v119
	v_pk_mul_f32 v[114:115], v[114:115], v[196:197] op_sel_hi:[1,0]
	v_pk_add_f32 v[120:121], v[124:125], 1.0 op_sel_hi:[1,0]
	v_ashrrev_i32_e32 v175, 31, v174
	v_rcp_f32_e32 v120, v120
	v_rcp_f32_e32 v121, v121
	v_pk_mul_f32 v[114:115], v[114:115], v[118:119]
	v_pk_mul_f32 v[108:109], v[112:113], v[108:109]
	v_cvt_pk_bf16_f32 v124, v114, v115
	v_pk_mul_f32 v[114:115], v[116:117], v[196:197] op_sel_hi:[1,0]
	v_lshlrev_b64 v[116:117], 1, v[174:175]
	v_pk_mul_f32 v[114:115], v[114:115], v[120:121]
	v_mul_f32_e32 v120, 0xbfb8aa3b, v197
	v_pk_mul_f32 v[110:111], v[110:111], v[120:121] op_sel_hi:[1,0]
	v_cvt_pk_bf16_f32 v125, v114, v115
	v_mov_b64_e32 v[114:115], s[16:17]
	v_exp_f32_e32 v110, v110
	v_exp_f32_e32 v111, v111
	v_pk_mul_f32 v[112:113], v[112:113], v[120:121] op_sel_hi:[1,0]
	v_mad_i64_i32 v[118:119], s[0:1], v195, s80, v[114:115]
	v_pk_add_f32 v[110:111], v[110:111], 1.0 op_sel_hi:[1,0]
	v_exp_f32_e32 v112, v112
	v_rcp_f32_e32 v110, v110
	v_rcp_f32_e32 v111, v111
	v_exp_f32_e32 v113, v113
	v_lshl_add_u64 v[118:119], v[118:119], 0, v[116:117]
	global_store_dwordx4 v[118:119], v[122:125], off
	v_mul_f32_e32 v118, v197, v197
	v_pk_mul_f32 v[106:107], v[106:107], v[118:119] op_sel_hi:[1,0]
	v_pk_mul_f32 v[102:103], v[102:103], v[120:121] op_sel_hi:[1,0]
	v_pk_mul_f32 v[106:107], v[106:107], v[110:111]
	v_pk_add_f32 v[110:111], v[112:113], 1.0 op_sel_hi:[1,0]
	v_exp_f32_e32 v102, v102
	v_rcp_f32_e32 v110, v110
	v_rcp_f32_e32 v111, v111
	v_exp_f32_e32 v103, v103
	v_pk_mul_f32 v[108:109], v[108:109], v[118:119] op_sel_hi:[1,0]
	v_cvt_pk_bf16_f32 v106, v106, v107
	v_pk_mul_f32 v[98:99], v[98:99], v[118:119] op_sel_hi:[1,0]
	v_pk_mul_f32 v[108:109], v[108:109], v[110:111]
	v_pk_add_f32 v[102:103], v[102:103], 1.0 op_sel_hi:[1,0]
	v_cvt_pk_bf16_f32 v107, v108, v109
	v_pk_mul_f32 v[108:109], v[104:105], v[120:121] op_sel_hi:[1,0]
	v_rcp_f32_e32 v102, v102
	v_rcp_f32_e32 v103, v103
	v_exp_f32_e32 v108, v108
	v_exp_f32_e32 v109, v109
	v_pk_mul_f32 v[100:101], v[104:105], v[100:101]
	v_pk_mul_f32 v[98:99], v[98:99], v[102:103]
	v_pk_mul_f32 v[92:93], v[96:97], v[92:93]
	v_pk_add_f32 v[104:105], v[108:109], 1.0 op_sel_hi:[1,0]
	v_cvt_pk_bf16_f32 v108, v98, v99
	v_pk_mul_f32 v[98:99], v[100:101], v[118:119] op_sel_hi:[1,0]
	v_mul_f32_e32 v100, 0xbfb8aa3b, v178
	v_rcp_f32_e32 v104, v104
	v_rcp_f32_e32 v105, v105
	v_pk_mul_f32 v[94:95], v[94:95], v[100:101] op_sel_hi:[1,0]
	v_pk_mul_f32 v[96:97], v[96:97], v[100:101] op_sel_hi:[1,0]
	v_exp_f32_e32 v94, v94
	v_exp_f32_e32 v95, v95
	v_pk_mul_f32 v[98:99], v[98:99], v[104:105]
	v_exp_f32_e32 v96, v96
	v_cvt_pk_bf16_f32 v109, v98, v99
	v_or_b32_e32 v98, 16, v195
	v_pk_add_f32 v[94:95], v[94:95], 1.0 op_sel_hi:[1,0]
	v_mad_i64_i32 v[98:99], s[0:1], v98, s80, v[114:115]
	v_rcp_f32_e32 v94, v94
	v_rcp_f32_e32 v95, v95
	v_exp_f32_e32 v97, v97
	v_lshl_add_u64 v[98:99], v[98:99], 0, v[116:117]
	global_store_dwordx4 v[98:99], v[106:109], off
	v_mul_f32_e32 v98, v178, v178
	v_pk_mul_f32 v[90:91], v[90:91], v[98:99] op_sel_hi:[1,0]
	v_pk_mul_f32 v[86:87], v[86:87], v[100:101] op_sel_hi:[1,0]
	v_pk_mul_f32 v[90:91], v[90:91], v[94:95]
	v_pk_add_f32 v[94:95], v[96:97], 1.0 op_sel_hi:[1,0]
	v_exp_f32_e32 v86, v86
	v_rcp_f32_e32 v94, v94
	v_rcp_f32_e32 v95, v95
	v_exp_f32_e32 v87, v87
	v_pk_mul_f32 v[92:93], v[92:93], v[98:99] op_sel_hi:[1,0]
	v_cvt_pk_bf16_f32 v90, v90, v91
; __device__ __forceinline__ unsigned cvt_pk_bf16(float lo, float hi) { unsigned r; asm volatile("v_cvt_pk_bf16_f32 %0, %1, %2" : "=v"(r) : "v"(lo), "v"(hi)); return r; }
;     __device__ __forceinline__ void operator()(Acc& acc, const Unit& u, int wr, int wc, int fr, int fq, LAS unsigned char*, const LAS float* rst) const {
;     ...
;         for (int ai = 0; ai < 2; ++ai)
; #pragma unroll
;             for (int m = 0; m < 4; ++m) {
;                 const int row = row0 + ai * 128 + m * 16; const float rs = rsv[ai][m];
;                 const float cexp = -1.4426950408889634f * rs, rs2 = rs * rs;
;                 unsigned w[4];
; #pragma unroll
;                 for (int n = 0; n < 2; ++n)
; #pragma unroll
;                     for (int p = 0; p < 2; ++p) { const f32x2 g2 = {acc[ai][0][m][n][2 * p], acc[ai][0][m][n][2 * p + 1]}, u2 = {acc[ai][1][m][n][2 * p], acc[ai][1][m][n][2 * p + 1]};
;                         f32x2 e2 = g2 * cexp; e2.x = __builtin_amdgcn_exp2f(e2.x); e2.y = __builtin_amdgcn_exp2f(e2.y);
;                         const f32x2 d2 = e2 + 1.0f; f32x2 r2; r2.x = __builtin_amdgcn_rcpf(d2.x); r2.y = __builtin_amdgcn_rcpf(d2.y);
;                         const f32x2 o2 = ((g2 * u2) * rs2) * r2; w[n * 2 + p] = cvt_pk_bf16(o2.x, o2.y); }
;                 *(u32x4*)(O + (size_t)row * FF + col0) = (u32x4){w[0], w[1], w[2], w[3]};
	v_pk_mul_f32 v[82:83], v[82:83], v[98:99] op_sel_hi:[1,0]
	v_pk_mul_f32 v[92:93], v[92:93], v[94:95]
	v_pk_add_f32 v[86:87], v[86:87], 1.0 op_sel_hi:[1,0]
	v_cvt_pk_bf16_f32 v91, v92, v93
	v_pk_mul_f32 v[92:93], v[88:89], v[100:101] op_sel_hi:[1,0]
	v_rcp_f32_e32 v86, v86
	v_rcp_f32_e32 v87, v87
	v_exp_f32_e32 v92, v92
	v_exp_f32_e32 v93, v93
	v_pk_mul_f32 v[84:85], v[88:89], v[84:85]
	v_pk_mul_f32 v[82:83], v[82:83], v[86:87]
	v_pk_mul_f32 v[76:77], v[80:81], v[76:77]
	v_pk_add_f32 v[88:89], v[92:93], 1.0 op_sel_hi:[1,0]
	v_cvt_pk_bf16_f32 v92, v82, v83
	v_pk_mul_f32 v[82:83], v[84:85], v[98:99] op_sel_hi:[1,0]
	v_mul_f32_e32 v84, 0xbfb8aa3b, v179
	v_rcp_f32_e32 v88, v88
	v_rcp_f32_e32 v89, v89
	v_pk_mul_f32 v[78:79], v[78:79], v[84:85] op_sel_hi:[1,0]
	v_pk_mul_f32 v[80:81], v[80:81], v[84:85] op_sel_hi:[1,0]
	v_exp_f32_e32 v78, v78
	v_exp_f32_e32 v79, v79
	v_pk_mul_f32 v[82:83], v[82:83], v[88:89]
	v_exp_f32_e32 v80, v80
	v_cvt_pk_bf16_f32 v93, v82, v83
	v_or_b32_e32 v82, 32, v195
	v_pk_add_f32 v[78:79], v[78:79], 1.0 op_sel_hi:[1,0]
	v_mad_i64_i32 v[82:83], s[0:1], v82, s80, v[114:115]
	v_rcp_f32_e32 v78, v78
	v_rcp_f32_e32 v79, v79
	v_exp_f32_e32 v81, v81
	v_lshl_add_u64 v[82:83], v[82:83], 0, v[116:117]
	global_store_dwordx4 v[82:83], v[90:93], off
	v_mul_f32_e32 v82, v179, v179
	v_pk_mul_f32 v[74:75], v[74:75], v[82:83] op_sel_hi:[1,0]
	v_pk_mul_f32 v[70:71], v[70:71], v[84:85] op_sel_hi:[1,0]
	v_pk_mul_f32 v[74:75], v[74:75], v[78:79]
	v_pk_add_f32 v[78:79], v[80:81], 1.0 op_sel_hi:[1,0]
	v_exp_f32_e32 v70, v70
	v_rcp_f32_e32 v78, v78
	v_rcp_f32_e32 v79, v79
	v_exp_f32_e32 v71, v71
	v_pk_mul_f32 v[76:77], v[76:77], v[82:83] op_sel_hi:[1,0]
	v_cvt_pk_bf16_f32 v74, v74, v75
	v_pk_mul_f32 v[66:67], v[66:67], v[82:83] op_sel_hi:[1,0]
	v_pk_mul_f32 v[76:77], v[76:77], v[78:79]
	v_pk_add_f32 v[70:71], v[70:71], 1.0 op_sel_hi:[1,0]
	v_cvt_pk_bf16_f32 v75, v76, v77
	v_pk_mul_f32 v[76:77], v[72:73], v[84:85] op_sel_hi:[1,0]
	v_rcp_f32_e32 v70, v70
	v_rcp_f32_e32 v71, v71
	v_exp_f32_e32 v76, v76
	v_exp_f32_e32 v77, v77
	v_pk_mul_f32 v[68:69], v[72:73], v[68:69]
	v_pk_mul_f32 v[66:67], v[66:67], v[70:71]
	v_pk_mul_f32 v[60:61], v[64:65], v[60:61]
	v_pk_add_f32 v[72:73], v[76:77], 1.0 op_sel_hi:[1,0]
	v_cvt_pk_bf16_f32 v76, v66, v67
	v_pk_mul_f32 v[66:67], v[68:69], v[82:83] op_sel_hi:[1,0]
	v_mul_f32_e32 v68, 0xbfb8aa3b, v176
	v_rcp_f32_e32 v72, v72
	v_rcp_f32_e32 v73, v73
	v_pk_mul_f32 v[62:63], v[62:63], v[68:69] op_sel_hi:[1,0]
	v_pk_mul_f32 v[64:65], v[64:65], v[68:69] op_sel_hi:[1,0]
	v_exp_f32_e32 v62, v62
	v_exp_f32_e32 v63, v63
	v_pk_mul_f32 v[66:67], v[66:67], v[72:73]
	v_exp_f32_e32 v64, v64
	v_cvt_pk_bf16_f32 v77, v66, v67
	v_or_b32_e32 v66, 48, v195
	v_pk_add_f32 v[62:63], v[62:63], 1.0 op_sel_hi:[1,0]
	v_mad_i64_i32 v[66:67], s[0:1], v66, s80, v[114:115]
	v_rcp_f32_e32 v62, v62
	v_rcp_f32_e32 v63, v63
	v_exp_f32_e32 v65, v65
	v_lshl_add_u64 v[66:67], v[66:67], 0, v[116:117]
	global_store_dwordx4 v[66:67], v[74:77], off
	v_add_u32_e32 v67, 0x80, v195
	v_mul_f32_e32 v66, v176, v176
	v_pk_mul_f32 v[58:59], v[58:59], v[66:67] op_sel_hi:[1,0]
	v_pk_mul_f32 v[54:55], v[54:55], v[68:69] op_sel_hi:[1,0]
	v_pk_mul_f32 v[58:59], v[58:59], v[62:63]
	v_pk_add_f32 v[62:63], v[64:65], 1.0 op_sel_hi:[1,0]
	v_exp_f32_e32 v54, v54
	v_rcp_f32_e32 v62, v62
	v_rcp_f32_e32 v63, v63
	v_exp_f32_e32 v55, v55
	v_pk_mul_f32 v[60:61], v[60:61], v[66:67] op_sel_hi:[1,0]
	v_cvt_pk_bf16_f32 v58, v58, v59
	v_pk_mul_f32 v[50:51], v[50:51], v[66:67] op_sel_hi:[1,0]
	v_pk_mul_f32 v[60:61], v[60:61], v[62:63]
	v_pk_add_f32 v[54:55], v[54:55], 1.0 op_sel_hi:[1,0]
	v_cvt_pk_bf16_f32 v59, v60, v61
	v_pk_mul_f32 v[60:61], v[56:57], v[68:69] op_sel_hi:[1,0]
	v_rcp_f32_e32 v54, v54
	v_rcp_f32_e32 v55, v55
	v_exp_f32_e32 v60, v60
	v_exp_f32_e32 v61, v61
	v_pk_mul_f32 v[52:53], v[56:57], v[52:53]
	v_pk_mul_f32 v[50:51], v[50:51], v[54:55]
	v_pk_mul_f32 v[44:45], v[48:49], v[44:45]
	v_pk_add_f32 v[56:57], v[60:61], 1.0 op_sel_hi:[1,0]
	v_cvt_pk_bf16_f32 v60, v50, v51
	v_pk_mul_f32 v[50:51], v[52:53], v[66:67] op_sel_hi:[1,0]
	v_mul_f32_e32 v52, 0xbfb8aa3b, v177
	v_pk_mul_f32 v[46:47], v[46:47], v[52:53] op_sel_hi:[1,0]
	v_rcp_f32_e32 v56, v56
	v_rcp_f32_e32 v57, v57
	v_exp_f32_e32 v46, v46
	v_exp_f32_e32 v47, v47
	v_pk_mul_f32 v[48:49], v[48:49], v[52:53] op_sel_hi:[1,0]
	v_pk_mul_f32 v[50:51], v[50:51], v[56:57]
	v_exp_f32_e32 v48, v48
	v_pk_add_f32 v[46:47], v[46:47], 1.0 op_sel_hi:[1,0]
	v_cvt_pk_bf16_f32 v61, v50, v51
	v_mad_i64_i32 v[50:51], s[0:1], v67, s80, v[114:115]
	v_rcp_f32_e32 v46, v46
	v_rcp_f32_e32 v47, v47
	v_exp_f32_e32 v49, v49
	v_lshl_add_u64 v[50:51], v[50:51], 0, v[116:117]
	global_store_dwordx4 v[50:51], v[58:61], off
	v_mul_f32_e32 v50, v177, v177
	v_pk_mul_f32 v[42:43], v[42:43], v[50:51] op_sel_hi:[1,0]
	v_pk_mul_f32 v[38:39], v[38:39], v[52:53] op_sel_hi:[1,0]
	v_pk_mul_f32 v[42:43], v[42:43], v[46:47]
	v_pk_add_f32 v[46:47], v[48:49], 1.0 op_sel_hi:[1,0]
	v_exp_f32_e32 v38, v38
	v_rcp_f32_e32 v46, v46
	v_rcp_f32_e32 v47, v47
	v_exp_f32_e32 v39, v39
	v_pk_mul_f32 v[44:45], v[44:45], v[50:51] op_sel_hi:[1,0]
	v_cvt_pk_bf16_f32 v42, v42, v43
	v_pk_mul_f32 v[34:35], v[34:35], v[50:51] op_sel_hi:[1,0]
	v_pk_mul_f32 v[44:45], v[44:45], v[46:47]
	v_pk_add_f32 v[38:39], v[38:39], 1.0 op_sel_hi:[1,0]
	v_cvt_pk_bf16_f32 v43, v44, v45
	v_pk_mul_f32 v[44:45], v[40:41], v[52:53] op_sel_hi:[1,0]
	v_rcp_f32_e32 v38, v38
	v_rcp_f32_e32 v39, v39
	v_exp_f32_e32 v44, v44
	v_exp_f32_e32 v45, v45
	v_pk_mul_f32 v[36:37], v[40:41], v[36:37]
	v_pk_mul_f32 v[34:35], v[34:35], v[38:39]
	v_pk_mul_f32 v[28:29], v[32:33], v[28:29]
	v_pk_add_f32 v[40:41], v[44:45], 1.0 op_sel_hi:[1,0]
	v_cvt_pk_bf16_f32 v44, v34, v35
	v_pk_mul_f32 v[34:35], v[36:37], v[50:51] op_sel_hi:[1,0]
	s_waitcnt lgkmcnt(0)
; __device__ __forceinline__ unsigned cvt_pk_bf16(float lo, float hi) { unsigned r; asm volatile("v_cvt_pk_bf16_f32 %0, %1, %2" : "=v"(r) : "v"(lo), "v"(hi)); return r; }
; __device__ __forceinline__ void rs_reduce(const RsLoad& L, float& r0, float& r1) {
;     const f32x4 t0 = (L.a0 + L.b0) + (L.c0 + L.d0), t1 = (L.a1 + L.b1) + (L.c1 + L.d1);
;     r0 = rsqrtf(((t0.x + t0.y) + (t0.z + t0.w)) * (1.0f / 1024.0f) + EPS); r1 = rsqrtf(((t1.x + t1.y) + (t1.z + t1.w)) * (1.0f / 1024.0f) + EPS);
; }
; __device__ __forceinline__ void rs_spread(float r0, float r1, int fr, float (&rs)[2][4]) {
;     __device__ __forceinline__ void operator()(Acc& acc, const Unit& u, int wr, int wc, int fr, int fq, LAS unsigned char*, const LAS float* rst) const {
;     ...
;                     for (int p = 0; p < 2; ++p) { const f32x2 g2 = {acc[ai][0][m][n][2 * p], acc[ai][0][m][n][2 * p + 1]}, u2 = {acc[ai][1][m][n][2 * p], acc[ai][1][m][n][2 * p + 1]};
;                         f32x2 e2 = g2 * cexp; e2.x = __builtin_amdgcn_exp2f(e2.x); e2.y = __builtin_amdgcn_exp2f(e2.y);
;                         const f32x2 d2 = e2 + 1.0f; f32x2 r2; r2.x = __builtin_amdgcn_rcpf(d2.x); r2.y = __builtin_amdgcn_rcpf(d2.y);
;                         const f32x2 o2 = ((g2 * u2) * rs2) * r2; w[n * 2 + p] = cvt_pk_bf16(o2.x, o2.y); }
;                 *(u32x4*)(O + (size_t)row * FF + col0) = (u32x4){w[0], w[1], w[2], w[3]};
	v_mul_f32_e32 v36, 0xbfb8aa3b, v126
	v_rcp_f32_e32 v40, v40
	v_rcp_f32_e32 v41, v41
	v_pk_mul_f32 v[30:31], v[30:31], v[36:37] op_sel_hi:[1,0]
	v_pk_mul_f32 v[32:33], v[32:33], v[36:37] op_sel_hi:[1,0]
	v_exp_f32_e32 v30, v30
	v_exp_f32_e32 v31, v31
	v_pk_mul_f32 v[34:35], v[34:35], v[40:41]
	v_exp_f32_e32 v32, v32
	v_cvt_pk_bf16_f32 v45, v34, v35
	v_add_u32_e32 v34, 0x90, v195
	v_pk_add_f32 v[30:31], v[30:31], 1.0 op_sel_hi:[1,0]
	v_mad_i64_i32 v[34:35], s[0:1], v34, s80, v[114:115]
	v_rcp_f32_e32 v30, v30
	v_rcp_f32_e32 v31, v31
	v_exp_f32_e32 v33, v33
	v_lshl_add_u64 v[34:35], v[34:35], 0, v[116:117]
	global_store_dwordx4 v[34:35], v[42:45], off
	v_mul_f32_e32 v34, v126, v126
	v_pk_mul_f32 v[26:27], v[26:27], v[34:35] op_sel_hi:[1,0]
	v_pk_mul_f32 v[22:23], v[22:23], v[36:37] op_sel_hi:[1,0]
	v_pk_mul_f32 v[26:27], v[26:27], v[30:31]
	v_pk_add_f32 v[30:31], v[32:33], 1.0 op_sel_hi:[1,0]
	v_exp_f32_e32 v22, v22
	v_rcp_f32_e32 v30, v30
	v_rcp_f32_e32 v31, v31
	v_exp_f32_e32 v23, v23
	v_pk_mul_f32 v[28:29], v[28:29], v[34:35] op_sel_hi:[1,0]
	v_cvt_pk_bf16_f32 v26, v26, v27
	v_pk_mul_f32 v[18:19], v[18:19], v[34:35] op_sel_hi:[1,0]
	v_pk_mul_f32 v[28:29], v[28:29], v[30:31]
	v_pk_add_f32 v[22:23], v[22:23], 1.0 op_sel_hi:[1,0]
	v_cvt_pk_bf16_f32 v27, v28, v29
	v_pk_mul_f32 v[28:29], v[24:25], v[36:37] op_sel_hi:[1,0]
	v_rcp_f32_e32 v22, v22
	v_rcp_f32_e32 v23, v23
	v_exp_f32_e32 v28, v28
	v_exp_f32_e32 v29, v29
	v_pk_mul_f32 v[20:21], v[24:25], v[20:21]
	v_pk_mul_f32 v[18:19], v[18:19], v[22:23]
	v_pk_mul_f32 v[10:11], v[14:15], v[10:11]
	v_pk_add_f32 v[24:25], v[28:29], 1.0 op_sel_hi:[1,0]
	v_cvt_pk_bf16_f32 v28, v18, v19
	v_pk_mul_f32 v[18:19], v[20:21], v[34:35] op_sel_hi:[1,0]
	v_mul_f32_e32 v20, 0xbfb8aa3b, v127
	v_rcp_f32_e32 v24, v24
	v_rcp_f32_e32 v25, v25
	v_pk_mul_f32 v[22:23], v[14:15], v[20:21] op_sel_hi:[1,0]
	v_pk_mul_f32 v[14:15], v[16:17], v[20:21] op_sel_hi:[1,0]
	v_exp_f32_e32 v22, v22
	v_exp_f32_e32 v14, v14
	v_exp_f32_e32 v15, v15
	v_exp_f32_e32 v23, v23
	v_pk_mul_f32 v[18:19], v[18:19], v[24:25]
	v_pk_mul_f32 v[12:13], v[16:17], v[12:13]
	v_cvt_pk_bf16_f32 v29, v18, v19
	v_add_u32_e32 v18, 0xa0, v195
	v_pk_add_f32 v[14:15], v[14:15], 1.0 op_sel_hi:[1,0]
	v_mad_i64_i32 v[18:19], s[0:1], v18, s80, v[114:115]
	v_rcp_f32_e32 v14, v14
	v_rcp_f32_e32 v15, v15
	v_lshl_add_u64 v[18:19], v[18:19], 0, v[116:117]
	v_pk_add_f32 v[22:23], v[22:23], 1.0 op_sel_hi:[1,0]
	global_store_dwordx4 v[18:19], v[26:29], off
	v_mul_f32_e32 v18, v127, v127
	v_rcp_f32_e32 v22, v22
	v_rcp_f32_e32 v23, v23
	v_pk_mul_f32 v[16:17], v[6:7], v[20:21] op_sel_hi:[1,0]
	v_pk_mul_f32 v[12:13], v[12:13], v[18:19] op_sel_hi:[1,0]
	v_exp_f32_e32 v16, v16
	v_exp_f32_e32 v17, v17
	v_pk_mul_f32 v[12:13], v[12:13], v[14:15]
	v_pk_mul_f32 v[14:15], v[8:9], v[20:21] op_sel_hi:[1,0]
	v_pk_mul_f32 v[10:11], v[10:11], v[18:19] op_sel_hi:[1,0]
	v_exp_f32_e32 v14, v14
	v_exp_f32_e32 v15, v15
	v_pk_mul_f32 v[10:11], v[10:11], v[22:23]
	v_pk_mul_f32 v[2:3], v[6:7], v[2:3]
	v_cvt_pk_bf16_f32 v10, v10, v11
	v_cvt_pk_bf16_f32 v11, v12, v13
	v_pk_add_f32 v[12:13], v[16:17], 1.0 op_sel_hi:[1,0]
	v_pk_add_f32 v[6:7], v[14:15], 1.0 op_sel_hi:[1,0]
	v_rcp_f32_e32 v12, v12
	v_rcp_f32_e32 v13, v13
	v_rcp_f32_e32 v6, v6
	v_rcp_f32_e32 v7, v7
	v_pk_mul_f32 v[2:3], v[2:3], v[18:19] op_sel_hi:[1,0]
	v_pk_mul_f32 v[4:5], v[8:9], v[4:5]
	v_pk_mul_f32 v[2:3], v[2:3], v[12:13]
	s_waitcnt vmcnt(7)
	v_pk_add_f32 v[8:9], v[148:149], v[152:153]
	v_cvt_pk_bf16_f32 v12, v2, v3
	v_pk_mul_f32 v[2:3], v[4:5], v[18:19] op_sel_hi:[1,0]
	v_pk_add_f32 v[4:5], v[156:157], v[160:161]
	v_pk_mul_f32 v[2:3], v[2:3], v[6:7]
	v_pk_add_f32 v[6:7], v[154:155], v[158:159]
	v_pk_add_f32 v[14:15], v[146:147], v[150:151]
	v_pk_add_f32 v[4:5], v[4:5], v[8:9]
	v_pk_add_f32 v[6:7], v[6:7], v[14:15]
	v_pk_add_f32 v[8:9], v[140:141], v[144:145]
	v_pk_add_f32 v[14:15], v[138:139], v[142:143]
	v_pk_add_f32 v[16:17], v[132:133], v[136:137]
	v_pk_add_f32 v[18:19], v[130:131], v[134:135]
	v_pk_add_f32 v[8:9], v[8:9], v[16:17]
	v_pk_add_f32 v[14:15], v[14:15], v[18:19]
	v_pk_mov_b32 v[16:17], v[6:7], v[4:5] op_sel:[1,0]
	v_mov_b32_e32 v7, v5
	v_pk_add_f32 v[4:5], v[16:17], v[6:7]
	v_pk_mov_b32 v[6:7], v[14:15], v[8:9] op_sel:[1,0]
	v_mov_b32_e32 v15, v9
	v_pk_add_f32 v[6:7], v[6:7], v[14:15]
	v_mov_b32_e32 v9, v4
	v_mov_b32_e32 v8, v6
	v_mov_b32_e32 v4, v7
	v_pk_add_f32 v[4:5], v[8:9], v[4:5]
	v_cvt_pk_bf16_f32 v13, v2, v3
	v_add_u32_e32 v2, 0xb0, v195
	v_pk_fma_f32 v[4:5], v[4:5], s[82:83], v[162:163] op_sel_hi:[1,0,0]
	v_mad_i64_i32 v[2:3], s[0:1], v2, s80, v[114:115]
	v_mul_f32_e32 v6, 0x4b800000, v5
	v_cmp_gt_f32_e32 vcc, s69, v5
	v_cmp_gt_f32_e64 s[0:1], s69, v4
	v_lshl_add_u64 v[2:3], v[2:3], 0, v[116:117]
	v_cndmask_b32_e32 v5, v5, v6, vcc
	v_mul_f32_e32 v6, 0x4b800000, v4
	v_cndmask_b32_e64 v4, v4, v6, s[0:1]
	v_rsq_f32_e32 v5, v5
	v_rsq_f32_e32 v4, v4
	global_store_dwordx4 v[2:3], v[10:13], off
	v_mul_f32_e32 v2, 0x45800000, v5
	v_mul_f32_e32 v3, 0x45800000, v4
	v_cndmask_b32_e32 v2, v5, v2, vcc
	v_cndmask_b32_e64 v3, v4, v3, s[0:1]
	ds_write2st64_b32 v181, v2, v3 offset1:1
	s_andn2_b64 vcc, exec, s[90:91]
	s_mov_b64 s[0:1], -1
	s_cbranch_vccnz .LBB0_766
